# AF32 GEMM tile prologue: counted vmcnt on the cross-tile-prefetch path (does not wait for the previous tile's epilogue stores)
# baseline (speedup 1.0000x reference)
; #define G_LOAD(kt_) do { \
;     if constexpr (AF32) { _Pragma("unroll") for (int i = 0; i < 4; ++i) ld16_sc1(ra[i], Af + (size_t)i * 32 * lda + (kt_) * 32); } \
;     else { _Pragma("unroll") for (int i = 0; i < 2; ++i) ld16_sc1(rab[i], Ab + (size_t)i * 64 * lda + (kt_) * 32); } \
;     _Pragma("unroll") for (int i = 0; i < 4; ++i) ld16_sc1(rb[i], Bp + (size_t)(kt_) * bstep + i * 2048); } while (0)
; template <bool AF32, class Epi>
; __device__ __forceinline__ void gemm_tile(unsigned char* smem, const void* Ap, int lda, const bf16_t* WT, int N, int K, const Epi& epi, int m0, int n0,
;                                           GPre& pr, bool preloaded, const void* nAp, int nn0, bool has_next) {
;     ...
;   const float* Af = (const float*)Ap + (size_t)(tid >> 3) * lda + (tid & 7) * 4;
;   const bf16_t* Ab = (const bf16_t*)Ap + (size_t)(tid >> 2) * lda + (tid & 3) * 8;
;   const bf16_t* Bp = WT + (size_t)n0 * 32 + tid * 8;
;   const size_t bstep = (size_t)N * 32;
;   const int awf = (tid >> 3) * GLD + (tid & 7) * 4;
;   const int awb = (tid >> 2) * GLD + (tid & 3) * 8;
;     ...
;   if (!preloaded) G_LOAD(0);
;   G_STORE(0);
.LBB0_293:
	s_ashr_i32 s47, s46, 31
	s_xor_b64 s[66:67], s[48:49], -1
	s_lshl_b64 s[52:53], s[46:47], 19
	v_mov_b32_e32 v18, v210
	s_add_u32 s54, s10, s52
	s_addc_u32 s55, s11, s53
	v_ashrrev_i32_e32 v180, 3, v18
	s_lshl_b32 s48, s51, 8
	v_ashrrev_i32_e32 v181, 31, v180
	v_lshlrev_b64 v[48:49], 12, v[180:181]
	s_ashr_i32 s49, s48, 31
	v_lshl_add_u64 v[16:17], s[54:55], 0, v[48:49]
	s_lshl_b64 s[54:55], s[48:49], 6
	v_and_b32_e32 v179, 7, v18
	v_lshlrev_b32_e32 v184, 3, v18
	s_add_u32 s68, s2, s54
	v_lshlrev_b32_e32 v176, 4, v179
	s_addc_u32 s69, s33, s55
	v_ashrrev_i32_e32 v185, 31, v184
	v_readfirstlane_b32 s47, v18
	v_lshl_add_u64 v[16:17], v[16:17], 0, v[176:177]
	s_andn2_b64 vcc, exec, s[66:67]
	v_lshl_add_u64 v[50:51], v[184:185], 1, s[68:69]
	s_cbranch_vccnz .LBB0_295
	global_load_dwordx4 v[40:43], v[16:17], off sc1
	v_lshl_add_u64 v[0:1], v[16:17], 0, s[14:15]
	global_load_dwordx4 v[44:47], v[0:1], off sc1
	v_lshl_add_u64 v[0:1], v[16:17], 0, s[16:17]
	global_load_dwordx4 v[32:35], v[0:1], off sc1
	v_lshl_add_u64 v[0:1], v[16:17], 0, s[18:19]
	global_load_dwordx4 v[36:39], v[0:1], off sc1
	global_load_dwordx4 v[0:3], v[50:51], off sc1
	v_lshl_add_u64 v[4:5], v[50:51], 0, s[20:21]
	global_load_dwordx4 v[4:7], v[4:5], off sc1
	v_lshl_add_u64 v[8:9], v[50:51], 0, s[22:23]
	global_load_dwordx4 v[8:11], v[8:9], off sc1
	v_lshl_add_u64 v[12:13], v[50:51], 0, s[24:25]
	global_load_dwordx4 v[12:15], v[12:13], off sc1
	s_waitcnt vmcnt(0)
; #define G_LOAD(kt_) do { \
;     if constexpr (AF32) { _Pragma("unroll") for (int i = 0; i < 4; ++i) ld16_sc1(ra[i], Af + (size_t)i * 32 * lda + (kt_) * 32); } \
;     else { _Pragma("unroll") for (int i = 0; i < 2; ++i) ld16_sc1(rab[i], Ab + (size_t)i * 64 * lda + (kt_) * 32); } \
;     _Pragma("unroll") for (int i = 0; i < 4; ++i) ld16_sc1(rb[i], Bp + (size_t)(kt_) * bstep + i * 2048); } while (0)
; template <bool AF32, class Epi>
; __device__ __forceinline__ void gemm_tile(unsigned char* smem, const void* Ap, int lda, const bf16_t* WT, int N, int K, const Epi& epi, int m0, int n0,
;                                           GPre& pr, bool preloaded, const void* nAp, int nn0, bool has_next) {
;     ...
; #pragma unroll
;   for (int m = 0; m < 4; ++m)
; #pragma unroll
;     for (int n = 0; n < 8; ++n) acc[m][n] = (f32x4){0.f, 0.f, 0.f, 0.f};
;     ...
;   if (!preloaded) G_LOAD(0);
;   G_STORE(0);
;   if (nk > 1) G_LOAD(1);
;   __syncthreads();
.LBB0_295:
	v_and_b32_e32 v52, 15, v18
	v_bfe_u32 v53, v18, 4, 2
	v_lshrrev_b32_e32 v19, 2, v18
	v_and_b32_e32 v18, 24, v184
	s_waitcnt vmcnt(32)
	v_mad_u64_u32 v[162:163], s[66:67], v19, 40, v[18:19]
	v_lshrrev_b32_e32 v250, 2, v210
	v_add_u32_e32 v251, 4, v250
	v_and_b32_e32 v251, 8, v251
	v_and_b32_e32 v252, 3, v210
	v_lshlrev_b32_e32 v252, 3, v252
	v_xor_b32_e32 v252, v252, v251
	v_mad_u32_u24 v162, v250, 40, v252
	v_cvt_pk_bf16_f32 v18, v40, v41
	v_mov_b32_e32 v21, v40
	v_mov_b32_e32 v40, v45
	v_mov_b32_e32 v20, v44
	v_pk_mul_f32 v[22:23], v[40:41], v[40:41]
	v_lshlrev_b32_e32 v190, 2, v179
	v_pk_fma_f32 v[20:21], v[20:21], v[20:21], v[22:23]
	v_mov_b32_e32 v22, v46
	v_mov_b32_e32 v23, v42
	v_mad_u64_u32 v[160:161], s[66:67], v180, 40, v[190:191]
	v_lshrrev_b32_e32 v250, 3, v210
	v_add_u32_e32 v251, 4, v250
	v_and_b32_e32 v251, 8, v251
	v_and_b32_e32 v252, 7, v210
	v_lshlrev_b32_e32 v252, 2, v252
	v_xor_b32_e32 v252, v252, v251
	v_mad_u32_u24 v160, v250, 40, v252
	v_cvt_pk_bf16_f32 v19, v42, v43
	v_pk_fma_f32 v[20:21], v[22:23], v[22:23], v[20:21]
	v_mov_b32_e32 v42, v47
	v_lshlrev_b32_e32 v161, 1, v160
	v_pk_fma_f32 v[186:187], v[42:43], v[42:43], v[20:21]
	v_cvt_pk_bf16_f32 v20, v44, v45
	v_cvt_pk_bf16_f32 v21, v46, v47
	ds_write2st64_b64 v161, v[18:19], v[20:21] offset1:5
	v_cvt_pk_bf16_f32 v18, v32, v33
	v_mov_b32_e32 v21, v32
	v_mov_b32_e32 v32, v37
	v_mov_b32_e32 v20, v36
	v_pk_mul_f32 v[22:23], v[32:33], v[32:33]
	v_cvt_pk_bf16_f32 v19, v34, v35
	v_pk_fma_f32 v[20:21], v[20:21], v[20:21], v[22:23]
	v_mov_b32_e32 v22, v38
	v_mov_b32_e32 v23, v34
	v_pk_fma_f32 v[20:21], v[22:23], v[22:23], v[20:21]
	v_mov_b32_e32 v34, v39
	v_pk_fma_f32 v[182:183], v[34:35], v[34:35], v[20:21]
	v_cvt_pk_bf16_f32 v20, v36, v37
	v_cvt_pk_bf16_f32 v21, v38, v39
	v_lshlrev_b32_e32 v163, 1, v162
	ds_write2st64_b64 v161, v[18:19], v[20:21] offset0:10 offset1:15
	ds_write_b128 v163, v[0:3] offset:10240
	ds_write_b128 v163, v[4:7] offset:15360
	ds_write_b128 v163, v[8:11] offset:20480
	ds_write_b128 v163, v[12:15] offset:25600
	v_lshl_add_u64 v[0:1], v[16:17], 0, s[26:27]
	global_load_dwordx4 v[28:31], v[0:1], off sc1
	v_lshl_add_u64 v[0:1], v[16:17], 0, s[28:29]
	global_load_dwordx4 v[24:27], v[0:1], off sc1
	v_lshl_add_u64 v[0:1], v[16:17], 0, s[30:31]
	s_ashr_i32 s3, s47, 1
	global_load_dwordx4 v[20:23], v[0:1], off sc1
	v_lshl_add_u64 v[0:1], v[16:17], 0, s[34:35]
	s_andn2_b32 s3, s3, 63
	v_lshlrev_b64 v[188:189], 10, v[180:181]
	global_load_dwordx4 v[16:19], v[0:1], off sc1
	v_lshl_add_u64 v[0:1], v[50:51], 0, s[36:37]
	v_or_b32_e32 v181, s3, v52
	s_lshl_b32 s3, s47, 1
	global_load_dwordx4 v[0:3], v[0:1], off sc1
	v_lshl_add_u64 v[4:5], v[50:51], 0, s[38:39]
	s_and_b32 s47, s3, 0x80
	global_load_dwordx4 v[4:7], v[4:5], off sc1
	v_lshl_add_u64 v[8:9], v[50:51], 0, s[40:41]
	v_or_b32_e32 v32, s47, v52
	global_load_dwordx4 v[8:11], v[8:9], off sc1
	v_lshl_add_u64 v[12:13], v[50:51], 0, s[42:43]
	v_mul_u32_u24_e32 v168, 0x50, v32
	v_lshl_add_u64 v[32:33], s[52:53], 0, v[48:49]
	global_load_dwordx4 v[12:15], v[12:13], off sc1
	s_add_u32 s54, s60, s54
	v_lshl_add_u64 v[32:33], v[32:33], 0, v[176:177]
	v_lshlrev_b32_e32 v178, 3, v53
	s_addc_u32 s55, s61, s55
	v_lshl_add_u64 v[166:167], s[12:13], 0, v[32:33]
	v_mov_b32_e32 v32, 0
	v_mul_lo_u32 v169, v181, s62
	v_lshl_add_u64 v[164:165], v[184:185], 1, s[54:55]
	s_mov_b32 s49, 0
	v_lshlrev_b32_e32 v170, 1, v178
	v_add_u32_e32 v250, 4, v210
	v_and_b32_e32 v250, 8, v250
	v_lshlrev_b32_e32 v250, 1, v250
	v_xor_b32_e32 v170, v170, v250
	v_mov_b32_e32 v33, v32
	v_mov_b32_e32 v34, v32
	v_mov_b32_e32 v35, v32
	v_mov_b32_e32 v36, v32
	v_mov_b32_e32 v37, v32
	v_mov_b32_e32 v38, v32
	v_mov_b32_e32 v39, v32
	v_mov_b32_e32 v40, v32
	v_mov_b32_e32 v41, v32
	v_mov_b32_e32 v42, v32
	v_mov_b32_e32 v43, v32
	v_mov_b32_e32 v44, v32
	v_mov_b32_e32 v45, v32
	v_mov_b32_e32 v46, v32
	v_mov_b32_e32 v47, v32
	v_mov_b32_e32 v52, v32
	v_mov_b32_e32 v53, v32
	v_mov_b32_e32 v54, v32
	v_mov_b32_e32 v55, v32
	v_mov_b32_e32 v60, v32
	v_mov_b32_e32 v61, v32
	v_mov_b32_e32 v62, v32
	v_mov_b32_e32 v63, v32
	v_mov_b32_e32 v68, v32
	v_mov_b32_e32 v69, v32
	v_mov_b32_e32 v70, v32
	v_mov_b32_e32 v71, v32
	v_mov_b32_e32 v76, v32
	v_mov_b32_e32 v77, v32
	v_mov_b32_e32 v78, v32
	v_mov_b32_e32 v79, v32
	v_mov_b32_e32 v48, v32
	v_mov_b32_e32 v49, v32
	v_mov_b32_e32 v50, v32
	v_mov_b32_e32 v51, v32
	v_mov_b32_e32 v56, v32
	v_mov_b32_e32 v57, v32
	v_mov_b32_e32 v58, v32
	v_mov_b32_e32 v59, v32
	v_mov_b32_e32 v64, v32
	v_mov_b32_e32 v65, v32
	v_mov_b32_e32 v66, v32
	v_mov_b32_e32 v67, v32
	v_mov_b32_e32 v72, v32
	v_mov_b32_e32 v73, v32
	v_mov_b32_e32 v74, v32
	v_mov_b32_e32 v75, v32
	v_mov_b32_e32 v84, v32
	v_mov_b32_e32 v85, v32
	v_mov_b32_e32 v86, v32
	v_mov_b32_e32 v87, v32
	v_mov_b32_e32 v92, v32
	v_mov_b32_e32 v93, v32
	v_mov_b32_e32 v94, v32
	v_mov_b32_e32 v95, v32
	v_mov_b32_e32 v100, v32
	v_mov_b32_e32 v101, v32
	v_mov_b32_e32 v102, v32
	v_mov_b32_e32 v103, v32
	v_mov_b32_e32 v108, v32
	v_mov_b32_e32 v109, v32
	v_mov_b32_e32 v110, v32
	v_mov_b32_e32 v111, v32
	v_mov_b32_e32 v80, v32
	v_mov_b32_e32 v81, v32
	v_mov_b32_e32 v82, v32
	v_mov_b32_e32 v83, v32
	v_mov_b32_e32 v88, v32
	v_mov_b32_e32 v89, v32
	v_mov_b32_e32 v90, v32
	v_mov_b32_e32 v91, v32
	v_mov_b32_e32 v96, v32
	v_mov_b32_e32 v97, v32
	v_mov_b32_e32 v98, v32
	v_mov_b32_e32 v99, v32
	v_mov_b32_e32 v104, v32
	v_mov_b32_e32 v105, v32
	v_mov_b32_e32 v106, v32
	v_mov_b32_e32 v107, v32
	v_mov_b32_e32 v116, v32
	v_mov_b32_e32 v117, v32
	v_mov_b32_e32 v118, v32
	v_mov_b32_e32 v119, v32
	v_mov_b32_e32 v124, v32
	v_mov_b32_e32 v125, v32
	v_mov_b32_e32 v126, v32
	v_mov_b32_e32 v127, v32
	v_mov_b32_e32 v136, v32
	v_mov_b32_e32 v137, v32
	v_mov_b32_e32 v138, v32
	v_mov_b32_e32 v139, v32
	v_mov_b32_e32 v140, v32
	v_mov_b32_e32 v141, v32
	v_mov_b32_e32 v142, v32
	v_mov_b32_e32 v143, v32
	v_mov_b32_e32 v112, v32
	v_mov_b32_e32 v113, v32
	v_mov_b32_e32 v114, v32
	v_mov_b32_e32 v115, v32
	v_mov_b32_e32 v120, v32
	v_mov_b32_e32 v121, v32
	v_mov_b32_e32 v122, v32
	v_mov_b32_e32 v123, v32
	v_mov_b32_e32 v128, v32
	v_mov_b32_e32 v129, v32
	v_mov_b32_e32 v130, v32
	v_mov_b32_e32 v131, v32
	v_mov_b32_e32 v132, v32
	v_mov_b32_e32 v133, v32
	v_mov_b32_e32 v134, v32
	v_mov_b32_e32 v135, v32
	v_mov_b32_e32 v144, v32
	v_mov_b32_e32 v145, v32
	v_mov_b32_e32 v146, v32
	v_mov_b32_e32 v147, v32
	v_mov_b32_e32 v148, v32
	v_mov_b32_e32 v149, v32
	v_mov_b32_e32 v150, v32
	v_mov_b32_e32 v151, v32
	v_mov_b32_e32 v152, v32
	v_mov_b32_e32 v153, v32
	v_mov_b32_e32 v154, v32
	v_mov_b32_e32 v155, v32
	v_mov_b32_e32 v156, v32
	v_mov_b32_e32 v157, v32
	v_mov_b32_e32 v158, v32
	v_mov_b32_e32 v159, v32
	s_waitcnt lgkmcnt(0)
	s_barrier

; #define G_LOAD(kt_) do { \
;     if constexpr (AF32) { _Pragma("unroll") for (int i = 0; i < 4; ++i) ld16_sc1(ra[i], Af + (size_t)i * 32 * lda + (kt_) * 32); } \
;     else { _Pragma("unroll") for (int i = 0; i < 2; ++i) ld16_sc1(rab[i], Ab + (size_t)i * 64 * lda + (kt_) * 32); } \
;     _Pragma("unroll") for (int i = 0; i < 4; ++i) ld16_sc1(rb[i], Bp + (size_t)(kt_) * bstep + i * 2048); } while (0)
; template <bool AF32, class Epi>
; __device__ __forceinline__ void gemm_tile(unsigned char* smem, const void* Ap, int lda, const bf16_t* WT, int N, int K, const Epi& epi, int m0, int n0,
;                                           GPre& pr, bool preloaded, const void* nAp, int nn0, bool has_next) {
;     ...
;   const float* Af = (const float*)Ap + (size_t)(tid >> 3) * lda + (tid & 7) * 4;
;   const bf16_t* Ab = (const bf16_t*)Ap + (size_t)(tid >> 2) * lda + (tid & 3) * 8;
;   const bf16_t* Bp = WT + (size_t)n0 * 32 + tid * 8;
;   const size_t bstep = (size_t)N * 32;
;   const int awf = (tid >> 3) * GLD + (tid & 7) * 4;
;   const int awb = (tid >> 2) * GLD + (tid & 3) * 8;
;     ...
;   if (!preloaded) G_LOAD(0);
.LBB0_386:
	s_ashr_i32 s49, s48, 31
	s_xor_b64 s[68:69], s[52:53], -1
	s_lshl_b64 s[52:53], s[48:49], 19
	v_mov_b32_e32 v34, v210
	s_add_u32 s54, s12, s52
	s_addc_u32 s55, s13, s53
	v_ashrrev_i32_e32 v178, 3, v34
	s_lshl_b32 s70, s66, 8
	v_ashrrev_i32_e32 v179, 31, v178
	v_lshlrev_b64 v[48:49], 12, v[178:179]
	s_ashr_i32 s71, s70, 31
	v_lshl_add_u64 v[32:33], s[54:55], 0, v[48:49]
	s_lshl_b64 s[54:55], s[70:71], 6
	v_and_b32_e32 v191, 7, v34
	v_lshlrev_b32_e32 v182, 3, v34
	s_add_u32 s70, s2, s54
	v_lshlrev_b32_e32 v176, 4, v191
	s_addc_u32 s71, s33, s55
	v_ashrrev_i32_e32 v183, 31, v182
	v_readfirstlane_b32 s49, v34
	v_lshl_add_u64 v[32:33], v[32:33], 0, v[176:177]
	s_andn2_b64 vcc, exec, s[68:69]
	v_lshl_add_u64 v[50:51], v[182:183], 1, s[70:71]
	s_cbranch_vccnz .LBB0_388
	global_load_dwordx4 v[24:27], v[32:33], off sc1
	v_lshl_add_u64 v[0:1], v[32:33], 0, s[16:17]
	global_load_dwordx4 v[28:31], v[0:1], off sc1
	v_lshl_add_u64 v[0:1], v[32:33], 0, s[18:19]
	global_load_dwordx4 v[16:19], v[0:1], off sc1
	v_lshl_add_u64 v[0:1], v[32:33], 0, s[20:21]
	global_load_dwordx4 v[20:23], v[0:1], off sc1
	global_load_dwordx4 v[0:3], v[50:51], off sc1
	v_lshl_add_u64 v[4:5], v[50:51], 0, s[22:23]
	global_load_dwordx4 v[4:7], v[4:5], off sc1
	v_lshl_add_u64 v[8:9], v[50:51], 0, s[24:25]
	global_load_dwordx4 v[8:11], v[8:9], off sc1
	v_lshl_add_u64 v[12:13], v[50:51], 0, s[26:27]
	global_load_dwordx4 v[12:15], v[12:13], off sc1
	s_waitcnt vmcnt(0)
; #define G_LOAD(kt_) do { \
;     if constexpr (AF32) { _Pragma("unroll") for (int i = 0; i < 4; ++i) ld16_sc1(ra[i], Af + (size_t)i * 32 * lda + (kt_) * 32); } \
;     else { _Pragma("unroll") for (int i = 0; i < 2; ++i) ld16_sc1(rab[i], Ab + (size_t)i * 64 * lda + (kt_) * 32); } \
;     _Pragma("unroll") for (int i = 0; i < 4; ++i) ld16_sc1(rb[i], Bp + (size_t)(kt_) * bstep + i * 2048); } while (0)
; template <bool AF32, class Epi>
; __device__ __forceinline__ void gemm_tile(unsigned char* smem, const void* Ap, int lda, const bf16_t* WT, int N, int K, const Epi& epi, int m0, int n0,
;                                           GPre& pr, bool preloaded, const void* nAp, int nn0, bool has_next) {
;     ...
; #pragma unroll
;   for (int m = 0; m < 4; ++m)
; #pragma unroll
;     for (int n = 0; n < 8; ++n) acc[m][n] = (f32x4){0.f, 0.f, 0.f, 0.f};
;     ...
;   if (!preloaded) G_LOAD(0);
;   G_STORE(0);
;   if (nk > 1) G_LOAD(1);
;   __syncthreads();
.LBB0_388:
	v_lshlrev_b64 v[186:187], 10, v[178:179]
	v_and_b32_e32 v52, 15, v34
	v_bfe_u32 v179, v34, 4, 2
	v_lshrrev_b32_e32 v35, 2, v34
	v_and_b32_e32 v34, 24, v182
	s_waitcnt vmcnt(16)
	v_mad_u64_u32 v[162:163], s[68:69], v35, 40, v[34:35]
	v_lshrrev_b32_e32 v250, 2, v210
	v_add_u32_e32 v251, 4, v250
	v_and_b32_e32 v251, 8, v251
	v_and_b32_e32 v252, 3, v210
	v_lshlrev_b32_e32 v252, 3, v252
	v_xor_b32_e32 v252, v252, v251
	v_mad_u32_u24 v162, v250, 40, v252
	v_cvt_pk_bf16_f32 v34, v24, v25
	v_mov_b32_e32 v37, v24
	v_mov_b32_e32 v24, v29
	v_mov_b32_e32 v36, v28
	v_pk_mul_f32 v[24:25], v[24:25], v[24:25]
	v_lshlrev_b32_e32 v188, 2, v191
	v_pk_fma_f32 v[24:25], v[36:37], v[36:37], v[24:25]
	v_mov_b32_e32 v36, v30
	v_mov_b32_e32 v37, v26
	v_mad_u64_u32 v[160:161], s[68:69], v178, 40, v[188:189]
	v_lshrrev_b32_e32 v250, 3, v210
	v_add_u32_e32 v251, 4, v250
	v_and_b32_e32 v251, 8, v251
	v_and_b32_e32 v252, 7, v210
	v_lshlrev_b32_e32 v252, 2, v252
	v_xor_b32_e32 v252, v252, v251
	v_mad_u32_u24 v160, v250, 40, v252
	v_cvt_pk_bf16_f32 v35, v26, v27
	v_pk_fma_f32 v[24:25], v[36:37], v[36:37], v[24:25]
	v_mov_b32_e32 v26, v31
	v_lshlrev_b32_e32 v161, 1, v160
	v_pk_fma_f32 v[184:185], v[26:27], v[26:27], v[24:25]
	v_cvt_pk_bf16_f32 v24, v28, v29
	v_cvt_pk_bf16_f32 v25, v30, v31
	ds_write2st64_b64 v161, v[34:35], v[24:25] offset1:5
	v_cvt_pk_bf16_f32 v24, v16, v17
	v_mov_b32_e32 v27, v16
	v_mov_b32_e32 v16, v21
	v_mov_b32_e32 v26, v20
	v_pk_mul_f32 v[16:17], v[16:17], v[16:17]
	v_cvt_pk_bf16_f32 v25, v18, v19
	v_pk_fma_f32 v[16:17], v[26:27], v[26:27], v[16:17]
	v_mov_b32_e32 v26, v22
	v_mov_b32_e32 v27, v18
	v_pk_fma_f32 v[16:17], v[26:27], v[26:27], v[16:17]
	v_mov_b32_e32 v18, v23
	v_pk_fma_f32 v[180:181], v[18:19], v[18:19], v[16:17]
	v_cvt_pk_bf16_f32 v16, v20, v21
	v_cvt_pk_bf16_f32 v17, v22, v23
	v_lshlrev_b32_e32 v163, 1, v162
	ds_write2st64_b64 v161, v[24:25], v[16:17] offset0:10 offset1:15
	ds_write_b128 v163, v[0:3] offset:10240
	ds_write_b128 v163, v[4:7] offset:15360
	ds_write_b128 v163, v[8:11] offset:20480
	ds_write_b128 v163, v[12:15] offset:25600
	v_lshl_add_u64 v[0:1], v[32:33], 0, s[28:29]
	global_load_dwordx4 v[44:47], v[0:1], off sc1
	v_lshl_add_u64 v[0:1], v[32:33], 0, s[30:31]
	global_load_dwordx4 v[40:43], v[0:1], off sc1
	v_lshl_add_u64 v[0:1], v[32:33], 0, s[34:35]
	s_ashr_i32 s3, s49, 1
	global_load_dwordx4 v[36:39], v[0:1], off sc1
	v_lshl_add_u64 v[0:1], v[32:33], 0, s[36:37]
	s_andn2_b32 s3, s3, 63
	global_load_dwordx4 v[32:35], v[0:1], off sc1
	v_lshl_add_u64 v[0:1], v[50:51], 0, s[38:39]
	v_or_b32_e32 v192, s3, v52
	s_lshl_b32 s3, s49, 1
	global_load_dwordx4 v[0:3], v[0:1], off sc1
	v_lshl_add_u64 v[4:5], v[50:51], 0, s[40:41]
	s_and_b32 s3, s3, 0x80
	global_load_dwordx4 v[4:7], v[4:5], off sc1
	v_lshl_add_u64 v[8:9], v[50:51], 0, s[42:43]
	v_or_b32_e32 v16, s3, v52
	global_load_dwordx4 v[8:11], v[8:9], off sc1
	v_lshl_add_u64 v[12:13], v[50:51], 0, s[44:45]
	v_mul_u32_u24_e32 v168, 0x50, v16
	v_lshl_add_u64 v[16:17], s[52:53], 0, v[48:49]
	global_load_dwordx4 v[12:15], v[12:13], off sc1
	s_add_u32 s54, s60, s54
	v_lshl_add_u64 v[16:17], v[16:17], 0, v[176:177]
	v_lshlrev_b32_e32 v18, 3, v179
	s_addc_u32 s55, s61, s55
	v_lshl_add_u64 v[166:167], s[14:15], 0, v[16:17]
	v_mov_b32_e32 v16, 0
	v_mul_lo_u32 v169, v192, s62
	v_lshl_add_u64 v[164:165], v[182:183], 1, s[54:55]
	s_mov_b32 s51, 0
	v_lshlrev_b32_e32 v170, 1, v18
	v_add_u32_e32 v250, 4, v210
	v_and_b32_e32 v250, 8, v250
	v_lshlrev_b32_e32 v250, 1, v250
	v_xor_b32_e32 v170, v170, v250
	v_mov_b32_e32 v17, v16
	v_mov_b32_e32 v18, v16
	v_mov_b32_e32 v19, v16
	v_mov_b32_e32 v20, v16
	v_mov_b32_e32 v21, v16
	v_mov_b32_e32 v22, v16
	v_mov_b32_e32 v23, v16
	v_mov_b32_e32 v24, v16
	v_mov_b32_e32 v25, v16
	v_mov_b32_e32 v26, v16
	v_mov_b32_e32 v27, v16
	v_mov_b32_e32 v28, v16
	v_mov_b32_e32 v29, v16
	v_mov_b32_e32 v30, v16
	v_mov_b32_e32 v31, v16
	v_mov_b32_e32 v52, v16
	v_mov_b32_e32 v53, v16
	v_mov_b32_e32 v54, v16
	v_mov_b32_e32 v55, v16
	v_mov_b32_e32 v60, v16
	v_mov_b32_e32 v61, v16
	v_mov_b32_e32 v62, v16
	v_mov_b32_e32 v63, v16
	v_mov_b32_e32 v68, v16
	v_mov_b32_e32 v69, v16
	v_mov_b32_e32 v70, v16
	v_mov_b32_e32 v71, v16
	v_mov_b32_e32 v76, v16
	v_mov_b32_e32 v77, v16
	v_mov_b32_e32 v78, v16
	v_mov_b32_e32 v79, v16
	v_mov_b32_e32 v48, v16
	v_mov_b32_e32 v49, v16
	v_mov_b32_e32 v50, v16
	v_mov_b32_e32 v51, v16
	v_mov_b32_e32 v56, v16
	v_mov_b32_e32 v57, v16
	v_mov_b32_e32 v58, v16
	v_mov_b32_e32 v59, v16
	v_mov_b32_e32 v64, v16
	v_mov_b32_e32 v65, v16
	v_mov_b32_e32 v66, v16
	v_mov_b32_e32 v67, v16
	v_mov_b32_e32 v72, v16
	v_mov_b32_e32 v73, v16
	v_mov_b32_e32 v74, v16
	v_mov_b32_e32 v75, v16
	v_mov_b32_e32 v84, v16
	v_mov_b32_e32 v85, v16
	v_mov_b32_e32 v86, v16
	v_mov_b32_e32 v87, v16
	v_mov_b32_e32 v92, v16
	v_mov_b32_e32 v93, v16
	v_mov_b32_e32 v94, v16
	v_mov_b32_e32 v95, v16
	v_mov_b32_e32 v100, v16
	v_mov_b32_e32 v101, v16
	v_mov_b32_e32 v102, v16
	v_mov_b32_e32 v103, v16
	v_mov_b32_e32 v108, v16
	v_mov_b32_e32 v109, v16
	v_mov_b32_e32 v110, v16
	v_mov_b32_e32 v111, v16
	v_mov_b32_e32 v80, v16
	v_mov_b32_e32 v81, v16
	v_mov_b32_e32 v82, v16
	v_mov_b32_e32 v83, v16
	v_mov_b32_e32 v88, v16
	v_mov_b32_e32 v89, v16
	v_mov_b32_e32 v90, v16
	v_mov_b32_e32 v91, v16
	v_mov_b32_e32 v96, v16
	v_mov_b32_e32 v97, v16
	v_mov_b32_e32 v98, v16
	v_mov_b32_e32 v99, v16
	v_mov_b32_e32 v104, v16
	v_mov_b32_e32 v105, v16
	v_mov_b32_e32 v106, v16
	v_mov_b32_e32 v107, v16
	v_mov_b32_e32 v116, v16
	v_mov_b32_e32 v117, v16
	v_mov_b32_e32 v118, v16
	v_mov_b32_e32 v119, v16
	v_mov_b32_e32 v124, v16
	v_mov_b32_e32 v125, v16
	v_mov_b32_e32 v126, v16
	v_mov_b32_e32 v127, v16
	v_mov_b32_e32 v136, v16
	v_mov_b32_e32 v137, v16
	v_mov_b32_e32 v138, v16
	v_mov_b32_e32 v139, v16
	v_mov_b32_e32 v140, v16
	v_mov_b32_e32 v141, v16
	v_mov_b32_e32 v142, v16
	v_mov_b32_e32 v143, v16
	v_mov_b32_e32 v112, v16
	v_mov_b32_e32 v113, v16
	v_mov_b32_e32 v114, v16
	v_mov_b32_e32 v115, v16
	v_mov_b32_e32 v120, v16
	v_mov_b32_e32 v121, v16
	v_mov_b32_e32 v122, v16
	v_mov_b32_e32 v123, v16
	v_mov_b32_e32 v128, v16
	v_mov_b32_e32 v129, v16
	v_mov_b32_e32 v130, v16
	v_mov_b32_e32 v131, v16
	v_mov_b32_e32 v132, v16
	v_mov_b32_e32 v133, v16
	v_mov_b32_e32 v134, v16
	v_mov_b32_e32 v135, v16
	v_mov_b32_e32 v144, v16
	v_mov_b32_e32 v145, v16
	v_mov_b32_e32 v146, v16
	v_mov_b32_e32 v147, v16
	v_mov_b32_e32 v148, v16
	v_mov_b32_e32 v149, v16
	v_mov_b32_e32 v150, v16
	v_mov_b32_e32 v151, v16
	v_mov_b32_e32 v152, v16
	v_mov_b32_e32 v153, v16
	v_mov_b32_e32 v154, v16
	v_mov_b32_e32 v155, v16
	v_mov_b32_e32 v156, v16
	v_mov_b32_e32 v157, v16
	v_mov_b32_e32 v158, v16
	v_mov_b32_e32 v159, v16
	s_waitcnt lgkmcnt(0)
	s_barrier

; #define G_LOAD(kt_) do { \
;     if constexpr (AF32) { _Pragma("unroll") for (int i = 0; i < 4; ++i) ld16_sc1(ra[i], Af + (size_t)i * 32 * lda + (kt_) * 32); } \
;     else { _Pragma("unroll") for (int i = 0; i < 2; ++i) ld16_sc1(rab[i], Ab + (size_t)i * 64 * lda + (kt_) * 32); } \
;     _Pragma("unroll") for (int i = 0; i < 4; ++i) ld16_sc1(rb[i], Bp + (size_t)(kt_) * bstep + i * 2048); } while (0)
; template <bool AF32, class Epi>
; __device__ __forceinline__ void gemm_tile(unsigned char* smem, const void* Ap, int lda, const bf16_t* WT, int N, int K, const Epi& epi, int m0, int n0,
;                                           GPre& pr, bool preloaded, const void* nAp, int nn0, bool has_next) {
;     ...
;   const float* Af = (const float*)Ap + (size_t)(tid >> 3) * lda + (tid & 7) * 4;
;   const bf16_t* Ab = (const bf16_t*)Ap + (size_t)(tid >> 2) * lda + (tid & 3) * 8;
;   const bf16_t* Bp = WT + (size_t)n0 * 32 + tid * 8;
;   const size_t bstep = (size_t)N * 32;
;   const int awf = (tid >> 3) * GLD + (tid & 7) * 4;
;   const int awb = (tid >> 2) * GLD + (tid & 3) * 8;
;     ...
;   if (!preloaded) G_LOAD(0);
.LBB0_457:
	s_ashr_i32 s49, s48, 31
	s_xor_b64 s[70:71], s[50:51], -1
	s_lshl_b64 s[54:55], s[48:49], 19
	v_mov_b32_e32 v18, v210
	s_add_u32 s56, s12, s54
	s_addc_u32 s57, s13, s55
	v_ashrrev_i32_e32 v180, 3, v18
	s_lshl_b32 s50, s53, 8
	v_ashrrev_i32_e32 v181, 31, v180
	v_lshlrev_b64 v[48:49], 12, v[180:181]
	s_ashr_i32 s51, s50, 31
	v_lshl_add_u64 v[16:17], s[56:57], 0, v[48:49]
	s_lshl_b64 s[56:57], s[50:51], 6
	v_and_b32_e32 v179, 7, v18
	v_lshlrev_b32_e32 v184, 3, v18
	s_add_u32 s72, s2, s56
	v_lshlrev_b32_e32 v176, 4, v179
	s_addc_u32 s73, s33, s57
	v_ashrrev_i32_e32 v185, 31, v184
	v_readfirstlane_b32 s49, v18
	v_lshl_add_u64 v[16:17], v[16:17], 0, v[176:177]
	s_andn2_b64 vcc, exec, s[70:71]
	v_lshl_add_u64 v[50:51], v[184:185], 1, s[72:73]
	s_cbranch_vccnz .LBB0_459
	global_load_dwordx4 v[40:43], v[16:17], off sc1
	v_lshl_add_u64 v[0:1], v[16:17], 0, s[16:17]
	global_load_dwordx4 v[44:47], v[0:1], off sc1
	v_lshl_add_u64 v[0:1], v[16:17], 0, s[18:19]
	global_load_dwordx4 v[32:35], v[0:1], off sc1
	v_lshl_add_u64 v[0:1], v[16:17], 0, s[20:21]
	global_load_dwordx4 v[36:39], v[0:1], off sc1
	global_load_dwordx4 v[0:3], v[50:51], off sc1
	v_lshl_add_u64 v[4:5], v[50:51], 0, s[22:23]
	global_load_dwordx4 v[4:7], v[4:5], off sc1
	v_lshl_add_u64 v[8:9], v[50:51], 0, s[24:25]
	global_load_dwordx4 v[8:11], v[8:9], off sc1
	v_lshl_add_u64 v[12:13], v[50:51], 0, s[26:27]
	global_load_dwordx4 v[12:15], v[12:13], off sc1
	s_waitcnt vmcnt(0)
; #define G_LOAD(kt_) do { \
;     if constexpr (AF32) { _Pragma("unroll") for (int i = 0; i < 4; ++i) ld16_sc1(ra[i], Af + (size_t)i * 32 * lda + (kt_) * 32); } \
;     else { _Pragma("unroll") for (int i = 0; i < 2; ++i) ld16_sc1(rab[i], Ab + (size_t)i * 64 * lda + (kt_) * 32); } \
;     _Pragma("unroll") for (int i = 0; i < 4; ++i) ld16_sc1(rb[i], Bp + (size_t)(kt_) * bstep + i * 2048); } while (0)
; template <bool AF32, class Epi>
; __device__ __forceinline__ void gemm_tile(unsigned char* smem, const void* Ap, int lda, const bf16_t* WT, int N, int K, const Epi& epi, int m0, int n0,
;                                           GPre& pr, bool preloaded, const void* nAp, int nn0, bool has_next) {
;     ...
; #pragma unroll
;   for (int m = 0; m < 4; ++m)
; #pragma unroll
;     for (int n = 0; n < 8; ++n) acc[m][n] = (f32x4){0.f, 0.f, 0.f, 0.f};
;     ...
;   if (!preloaded) G_LOAD(0);
;   G_STORE(0);
;   if (nk > 1) G_LOAD(1);
;   __syncthreads();
.LBB0_459:
	v_and_b32_e32 v52, 15, v18
	v_bfe_u32 v53, v18, 4, 2
	v_lshrrev_b32_e32 v19, 2, v18
	v_and_b32_e32 v18, 24, v184
	s_waitcnt vmcnt(32)
	v_mad_u64_u32 v[162:163], s[70:71], v19, 40, v[18:19]
	v_lshrrev_b32_e32 v250, 2, v210
	v_add_u32_e32 v251, 4, v250
	v_and_b32_e32 v251, 8, v251
	v_and_b32_e32 v252, 3, v210
	v_lshlrev_b32_e32 v252, 3, v252
	v_xor_b32_e32 v252, v252, v251
	v_mad_u32_u24 v162, v250, 40, v252
	v_cvt_pk_bf16_f32 v18, v40, v41
	v_mov_b32_e32 v21, v40
	v_mov_b32_e32 v40, v45
	v_mov_b32_e32 v20, v44
	v_pk_mul_f32 v[22:23], v[40:41], v[40:41]
	v_lshlrev_b32_e32 v190, 2, v179
	v_pk_fma_f32 v[20:21], v[20:21], v[20:21], v[22:23]
	v_mov_b32_e32 v22, v46
	v_mov_b32_e32 v23, v42
	v_mad_u64_u32 v[160:161], s[70:71], v180, 40, v[190:191]
	v_lshrrev_b32_e32 v250, 3, v210
	v_add_u32_e32 v251, 4, v250
	v_and_b32_e32 v251, 8, v251
	v_and_b32_e32 v252, 7, v210
	v_lshlrev_b32_e32 v252, 2, v252
	v_xor_b32_e32 v252, v252, v251
	v_mad_u32_u24 v160, v250, 40, v252
	v_cvt_pk_bf16_f32 v19, v42, v43
	v_pk_fma_f32 v[20:21], v[22:23], v[22:23], v[20:21]
	v_mov_b32_e32 v42, v47
	v_lshlrev_b32_e32 v161, 1, v160
	v_pk_fma_f32 v[186:187], v[42:43], v[42:43], v[20:21]
	v_cvt_pk_bf16_f32 v20, v44, v45
	v_cvt_pk_bf16_f32 v21, v46, v47
	ds_write2st64_b64 v161, v[18:19], v[20:21] offset1:5
	v_cvt_pk_bf16_f32 v18, v32, v33
	v_mov_b32_e32 v21, v32
	v_mov_b32_e32 v32, v37
	v_mov_b32_e32 v20, v36
	v_pk_mul_f32 v[22:23], v[32:33], v[32:33]
	v_cvt_pk_bf16_f32 v19, v34, v35
	v_pk_fma_f32 v[20:21], v[20:21], v[20:21], v[22:23]
	v_mov_b32_e32 v22, v38
	v_mov_b32_e32 v23, v34
	v_pk_fma_f32 v[20:21], v[22:23], v[22:23], v[20:21]
	v_mov_b32_e32 v34, v39
	v_pk_fma_f32 v[182:183], v[34:35], v[34:35], v[20:21]
	v_cvt_pk_bf16_f32 v20, v36, v37
	v_cvt_pk_bf16_f32 v21, v38, v39
	v_lshlrev_b32_e32 v163, 1, v162
	ds_write2st64_b64 v161, v[18:19], v[20:21] offset0:10 offset1:15
	ds_write_b128 v163, v[0:3] offset:10240
	ds_write_b128 v163, v[4:7] offset:15360
	ds_write_b128 v163, v[8:11] offset:20480
	ds_write_b128 v163, v[12:15] offset:25600
	v_lshl_add_u64 v[0:1], v[16:17], 0, s[28:29]
	global_load_dwordx4 v[28:31], v[0:1], off sc1
	v_lshl_add_u64 v[0:1], v[16:17], 0, s[30:31]
	global_load_dwordx4 v[24:27], v[0:1], off sc1
	v_lshl_add_u64 v[0:1], v[16:17], 0, s[34:35]
	s_ashr_i32 s3, s49, 1
	global_load_dwordx4 v[20:23], v[0:1], off sc1
	v_lshl_add_u64 v[0:1], v[16:17], 0, s[36:37]
	s_andn2_b32 s3, s3, 63
	v_lshlrev_b64 v[188:189], 10, v[180:181]
	global_load_dwordx4 v[16:19], v[0:1], off sc1
	v_lshl_add_u64 v[0:1], v[50:51], 0, s[38:39]
	v_or_b32_e32 v181, s3, v52
	s_lshl_b32 s3, s49, 1
	global_load_dwordx4 v[0:3], v[0:1], off sc1
	v_lshl_add_u64 v[4:5], v[50:51], 0, s[40:41]
	s_and_b32 s49, s3, 0x80
	global_load_dwordx4 v[4:7], v[4:5], off sc1
	v_lshl_add_u64 v[8:9], v[50:51], 0, s[42:43]
	v_or_b32_e32 v32, s49, v52
	global_load_dwordx4 v[8:11], v[8:9], off sc1
	v_lshl_add_u64 v[12:13], v[50:51], 0, s[44:45]
	v_mul_u32_u24_e32 v168, 0x50, v32
	v_lshl_add_u64 v[32:33], s[54:55], 0, v[48:49]
	global_load_dwordx4 v[12:15], v[12:13], off sc1
	s_add_u32 s56, s63, s56
	v_lshl_add_u64 v[32:33], v[32:33], 0, v[176:177]
	v_lshlrev_b32_e32 v178, 3, v53
	s_addc_u32 s57, s64, s57
	v_lshl_add_u64 v[166:167], s[14:15], 0, v[32:33]
	v_mov_b32_e32 v32, 0
	v_mul_lo_u32 v169, v181, s65
	v_lshl_add_u64 v[164:165], v[184:185], 1, s[56:57]
	s_mov_b32 s51, 0
	v_lshlrev_b32_e32 v170, 1, v178
	v_add_u32_e32 v250, 4, v210
	v_and_b32_e32 v250, 8, v250
	v_lshlrev_b32_e32 v250, 1, v250
	v_xor_b32_e32 v170, v170, v250
	v_mov_b32_e32 v33, v32
	v_mov_b32_e32 v34, v32
	v_mov_b32_e32 v35, v32
	v_mov_b32_e32 v36, v32
	v_mov_b32_e32 v37, v32
	v_mov_b32_e32 v38, v32
	v_mov_b32_e32 v39, v32
	v_mov_b32_e32 v40, v32
	v_mov_b32_e32 v41, v32
	v_mov_b32_e32 v42, v32
	v_mov_b32_e32 v43, v32
	v_mov_b32_e32 v44, v32
	v_mov_b32_e32 v45, v32
	v_mov_b32_e32 v46, v32
	v_mov_b32_e32 v47, v32
	v_mov_b32_e32 v52, v32
	v_mov_b32_e32 v53, v32
	v_mov_b32_e32 v54, v32
	v_mov_b32_e32 v55, v32
	v_mov_b32_e32 v60, v32
	v_mov_b32_e32 v61, v32
	v_mov_b32_e32 v62, v32
	v_mov_b32_e32 v63, v32
	v_mov_b32_e32 v68, v32
	v_mov_b32_e32 v69, v32
	v_mov_b32_e32 v70, v32
	v_mov_b32_e32 v71, v32
	v_mov_b32_e32 v76, v32
	v_mov_b32_e32 v77, v32
	v_mov_b32_e32 v78, v32
	v_mov_b32_e32 v79, v32
	v_mov_b32_e32 v48, v32
	v_mov_b32_e32 v49, v32
	v_mov_b32_e32 v50, v32
	v_mov_b32_e32 v51, v32
	v_mov_b32_e32 v56, v32
	v_mov_b32_e32 v57, v32
	v_mov_b32_e32 v58, v32
	v_mov_b32_e32 v59, v32
	v_mov_b32_e32 v64, v32
	v_mov_b32_e32 v65, v32
	v_mov_b32_e32 v66, v32
	v_mov_b32_e32 v67, v32
	v_mov_b32_e32 v72, v32
	v_mov_b32_e32 v73, v32
	v_mov_b32_e32 v74, v32
	v_mov_b32_e32 v75, v32
	v_mov_b32_e32 v84, v32
	v_mov_b32_e32 v85, v32
	v_mov_b32_e32 v86, v32
	v_mov_b32_e32 v87, v32
	v_mov_b32_e32 v92, v32
	v_mov_b32_e32 v93, v32
	v_mov_b32_e32 v94, v32
	v_mov_b32_e32 v95, v32
	v_mov_b32_e32 v100, v32
	v_mov_b32_e32 v101, v32
	v_mov_b32_e32 v102, v32
	v_mov_b32_e32 v103, v32
	v_mov_b32_e32 v108, v32
	v_mov_b32_e32 v109, v32
	v_mov_b32_e32 v110, v32
	v_mov_b32_e32 v111, v32
	v_mov_b32_e32 v80, v32
	v_mov_b32_e32 v81, v32
	v_mov_b32_e32 v82, v32
	v_mov_b32_e32 v83, v32
	v_mov_b32_e32 v88, v32
	v_mov_b32_e32 v89, v32
	v_mov_b32_e32 v90, v32
	v_mov_b32_e32 v91, v32
	v_mov_b32_e32 v96, v32
	v_mov_b32_e32 v97, v32
	v_mov_b32_e32 v98, v32
	v_mov_b32_e32 v99, v32
	v_mov_b32_e32 v104, v32
	v_mov_b32_e32 v105, v32
	v_mov_b32_e32 v106, v32
	v_mov_b32_e32 v107, v32
	v_mov_b32_e32 v116, v32
	v_mov_b32_e32 v117, v32
	v_mov_b32_e32 v118, v32
	v_mov_b32_e32 v119, v32
	v_mov_b32_e32 v124, v32
	v_mov_b32_e32 v125, v32
	v_mov_b32_e32 v126, v32
	v_mov_b32_e32 v127, v32
	v_mov_b32_e32 v136, v32
	v_mov_b32_e32 v137, v32
	v_mov_b32_e32 v138, v32
	v_mov_b32_e32 v139, v32
	v_mov_b32_e32 v140, v32
	v_mov_b32_e32 v141, v32
	v_mov_b32_e32 v142, v32
	v_mov_b32_e32 v143, v32
	v_mov_b32_e32 v112, v32
	v_mov_b32_e32 v113, v32
	v_mov_b32_e32 v114, v32
	v_mov_b32_e32 v115, v32
	v_mov_b32_e32 v120, v32
	v_mov_b32_e32 v121, v32
	v_mov_b32_e32 v122, v32
	v_mov_b32_e32 v123, v32
	v_mov_b32_e32 v128, v32
	v_mov_b32_e32 v129, v32
	v_mov_b32_e32 v130, v32
	v_mov_b32_e32 v131, v32
	v_mov_b32_e32 v132, v32
	v_mov_b32_e32 v133, v32
	v_mov_b32_e32 v134, v32
	v_mov_b32_e32 v135, v32
	v_mov_b32_e32 v144, v32
	v_mov_b32_e32 v145, v32
	v_mov_b32_e32 v146, v32
	v_mov_b32_e32 v147, v32
	v_mov_b32_e32 v148, v32
	v_mov_b32_e32 v149, v32
	v_mov_b32_e32 v150, v32
	v_mov_b32_e32 v151, v32
	v_mov_b32_e32 v152, v32
	v_mov_b32_e32 v153, v32
	v_mov_b32_e32 v154, v32
	v_mov_b32_e32 v155, v32
	v_mov_b32_e32 v156, v32
	v_mov_b32_e32 v157, v32
	v_mov_b32_e32 v158, v32
	v_mov_b32_e32 v159, v32
	s_waitcnt lgkmcnt(0)
	s_barrier

; #define G_LOAD(kt_) do { \
;     if constexpr (AF32) { _Pragma("unroll") for (int i = 0; i < 4; ++i) ld16_sc1(ra[i], Af + (size_t)i * 32 * lda + (kt_) * 32); } \
;     else { _Pragma("unroll") for (int i = 0; i < 2; ++i) ld16_sc1(rab[i], Ab + (size_t)i * 64 * lda + (kt_) * 32); } \
;     _Pragma("unroll") for (int i = 0; i < 4; ++i) ld16_sc1(rb[i], Bp + (size_t)(kt_) * bstep + i * 2048); } while (0)
; template <bool AF32, class Epi>
; __device__ __forceinline__ void gemm_tile(unsigned char* smem, const void* Ap, int lda, const bf16_t* WT, int N, int K, const Epi& epi, int m0, int n0,
;                                           GPre& pr, bool preloaded, const void* nAp, int nn0, bool has_next) {
;     ...
;   const float* Af = (const float*)Ap + (size_t)(tid >> 3) * lda + (tid & 7) * 4;
;   const bf16_t* Ab = (const bf16_t*)Ap + (size_t)(tid >> 2) * lda + (tid & 3) * 8;
;   const bf16_t* Bp = WT + (size_t)n0 * 32 + tid * 8;
;   const size_t bstep = (size_t)N * 32;
;   const int awf = (tid >> 3) * GLD + (tid & 7) * 4;
;   const int awb = (tid >> 2) * GLD + (tid & 3) * 8;
;     ...
;   if (!preloaded) G_LOAD(0);
.LBB0_675:
	s_ashr_i32 s47, s46, 31
	s_xor_b64 s[66:67], s[50:51], -1
	s_lshl_b64 s[50:51], s[46:47], 19
	v_mov_b32_e32 v34, v210
	s_add_u32 s52, s10, s50
	s_addc_u32 s53, s11, s51
	v_ashrrev_i32_e32 v178, 3, v34
	s_lshl_b32 s68, s64, 8
	v_ashrrev_i32_e32 v179, 31, v178
	v_lshlrev_b64 v[48:49], 12, v[178:179]
	s_ashr_i32 s69, s68, 31
	v_lshl_add_u64 v[32:33], s[52:53], 0, v[48:49]
	s_lshl_b64 s[52:53], s[68:69], 6
	v_and_b32_e32 v191, 7, v34
	v_lshlrev_b32_e32 v182, 3, v34
	s_add_u32 s68, s2, s52
	v_lshlrev_b32_e32 v176, 4, v191
	s_addc_u32 s69, s33, s53
	v_ashrrev_i32_e32 v183, 31, v182
	v_readfirstlane_b32 s47, v34
	v_lshl_add_u64 v[32:33], v[32:33], 0, v[176:177]
	s_andn2_b64 vcc, exec, s[66:67]
	v_lshl_add_u64 v[50:51], v[182:183], 1, s[68:69]
	s_cbranch_vccnz .LBB0_677
	global_load_dwordx4 v[24:27], v[32:33], off sc1
	v_lshl_add_u64 v[0:1], v[32:33], 0, s[14:15]
	global_load_dwordx4 v[28:31], v[0:1], off sc1
	v_lshl_add_u64 v[0:1], v[32:33], 0, s[16:17]
	global_load_dwordx4 v[16:19], v[0:1], off sc1
	v_lshl_add_u64 v[0:1], v[32:33], 0, s[18:19]
	global_load_dwordx4 v[20:23], v[0:1], off sc1
	global_load_dwordx4 v[0:3], v[50:51], off sc1
	v_lshl_add_u64 v[4:5], v[50:51], 0, s[20:21]
	global_load_dwordx4 v[4:7], v[4:5], off sc1
	v_lshl_add_u64 v[8:9], v[50:51], 0, s[22:23]
	global_load_dwordx4 v[8:11], v[8:9], off sc1
	v_lshl_add_u64 v[12:13], v[50:51], 0, s[24:25]
	global_load_dwordx4 v[12:15], v[12:13], off sc1
	s_waitcnt vmcnt(0)
; #define G_LOAD(kt_) do { \
;     if constexpr (AF32) { _Pragma("unroll") for (int i = 0; i < 4; ++i) ld16_sc1(ra[i], Af + (size_t)i * 32 * lda + (kt_) * 32); } \
;     else { _Pragma("unroll") for (int i = 0; i < 2; ++i) ld16_sc1(rab[i], Ab + (size_t)i * 64 * lda + (kt_) * 32); } \
;     _Pragma("unroll") for (int i = 0; i < 4; ++i) ld16_sc1(rb[i], Bp + (size_t)(kt_) * bstep + i * 2048); } while (0)
; template <bool AF32, class Epi>
; __device__ __forceinline__ void gemm_tile(unsigned char* smem, const void* Ap, int lda, const bf16_t* WT, int N, int K, const Epi& epi, int m0, int n0,
;                                           GPre& pr, bool preloaded, const void* nAp, int nn0, bool has_next) {
;     ...
; #pragma unroll
;   for (int m = 0; m < 4; ++m)
; #pragma unroll
;     for (int n = 0; n < 8; ++n) acc[m][n] = (f32x4){0.f, 0.f, 0.f, 0.f};
;     ...
;   if (!preloaded) G_LOAD(0);
;   G_STORE(0);
;   if (nk > 1) G_LOAD(1);
;   __syncthreads();
.LBB0_677:
	v_lshlrev_b64 v[186:187], 10, v[178:179]
	v_and_b32_e32 v52, 15, v34
	v_bfe_u32 v179, v34, 4, 2
	v_lshrrev_b32_e32 v35, 2, v34
	v_and_b32_e32 v34, 24, v182
	s_waitcnt vmcnt(16)
	v_mad_u64_u32 v[162:163], s[66:67], v35, 40, v[34:35]
	v_lshrrev_b32_e32 v250, 2, v210
	v_add_u32_e32 v251, 4, v250
	v_and_b32_e32 v251, 8, v251
	v_and_b32_e32 v252, 3, v210
	v_lshlrev_b32_e32 v252, 3, v252
	v_xor_b32_e32 v252, v252, v251
	v_mad_u32_u24 v162, v250, 40, v252
	v_cvt_pk_bf16_f32 v34, v24, v25
	v_mov_b32_e32 v37, v24
	v_mov_b32_e32 v24, v29
	v_mov_b32_e32 v36, v28
	v_pk_mul_f32 v[24:25], v[24:25], v[24:25]
	v_lshlrev_b32_e32 v188, 2, v191
	v_pk_fma_f32 v[24:25], v[36:37], v[36:37], v[24:25]
	v_mov_b32_e32 v36, v30
	v_mov_b32_e32 v37, v26
	v_mad_u64_u32 v[160:161], s[66:67], v178, 40, v[188:189]
	v_lshrrev_b32_e32 v250, 3, v210
	v_add_u32_e32 v251, 4, v250
	v_and_b32_e32 v251, 8, v251
	v_and_b32_e32 v252, 7, v210
	v_lshlrev_b32_e32 v252, 2, v252
	v_xor_b32_e32 v252, v252, v251
	v_mad_u32_u24 v160, v250, 40, v252
	v_cvt_pk_bf16_f32 v35, v26, v27
	v_pk_fma_f32 v[24:25], v[36:37], v[36:37], v[24:25]
	v_mov_b32_e32 v26, v31
	v_lshlrev_b32_e32 v161, 1, v160
	v_pk_fma_f32 v[184:185], v[26:27], v[26:27], v[24:25]
	v_cvt_pk_bf16_f32 v24, v28, v29
	v_cvt_pk_bf16_f32 v25, v30, v31
	ds_write2st64_b64 v161, v[34:35], v[24:25] offset1:5
	v_cvt_pk_bf16_f32 v24, v16, v17
	v_mov_b32_e32 v27, v16
	v_mov_b32_e32 v16, v21
	v_mov_b32_e32 v26, v20
	v_pk_mul_f32 v[16:17], v[16:17], v[16:17]
	v_cvt_pk_bf16_f32 v25, v18, v19
	v_pk_fma_f32 v[16:17], v[26:27], v[26:27], v[16:17]
	v_mov_b32_e32 v26, v22
	v_mov_b32_e32 v27, v18
	v_pk_fma_f32 v[16:17], v[26:27], v[26:27], v[16:17]
	v_mov_b32_e32 v18, v23
	v_pk_fma_f32 v[180:181], v[18:19], v[18:19], v[16:17]
	v_cvt_pk_bf16_f32 v16, v20, v21
	v_cvt_pk_bf16_f32 v17, v22, v23
	v_lshlrev_b32_e32 v163, 1, v162
	ds_write2st64_b64 v161, v[24:25], v[16:17] offset0:10 offset1:15
	ds_write_b128 v163, v[0:3] offset:10240
	ds_write_b128 v163, v[4:7] offset:15360
	ds_write_b128 v163, v[8:11] offset:20480
	ds_write_b128 v163, v[12:15] offset:25600
	v_lshl_add_u64 v[0:1], v[32:33], 0, s[26:27]
	global_load_dwordx4 v[44:47], v[0:1], off sc1
	v_lshl_add_u64 v[0:1], v[32:33], 0, s[28:29]
	global_load_dwordx4 v[40:43], v[0:1], off sc1
	v_lshl_add_u64 v[0:1], v[32:33], 0, s[30:31]
	s_ashr_i32 s3, s47, 1
	global_load_dwordx4 v[36:39], v[0:1], off sc1
	v_lshl_add_u64 v[0:1], v[32:33], 0, s[34:35]
	s_andn2_b32 s3, s3, 63
	global_load_dwordx4 v[32:35], v[0:1], off sc1
	v_lshl_add_u64 v[0:1], v[50:51], 0, s[36:37]
	v_or_b32_e32 v192, s3, v52
	s_lshl_b32 s3, s47, 1
	global_load_dwordx4 v[0:3], v[0:1], off sc1
	v_lshl_add_u64 v[4:5], v[50:51], 0, s[38:39]
	s_and_b32 s3, s3, 0x80
	global_load_dwordx4 v[4:7], v[4:5], off sc1
	v_lshl_add_u64 v[8:9], v[50:51], 0, s[40:41]
	v_or_b32_e32 v16, s3, v52
	global_load_dwordx4 v[8:11], v[8:9], off sc1
	v_lshl_add_u64 v[12:13], v[50:51], 0, s[42:43]
	v_mul_u32_u24_e32 v168, 0x50, v16
	v_lshl_add_u64 v[16:17], s[50:51], 0, v[48:49]
	global_load_dwordx4 v[12:15], v[12:13], off sc1
	s_add_u32 s52, s58, s52
	v_lshl_add_u64 v[16:17], v[16:17], 0, v[176:177]
	v_lshlrev_b32_e32 v18, 3, v179
	s_addc_u32 s53, s59, s53
	v_lshl_add_u64 v[166:167], s[12:13], 0, v[16:17]
	v_mov_b32_e32 v16, 0
	v_mul_lo_u32 v169, v192, s60
	v_lshl_add_u64 v[164:165], v[182:183], 1, s[52:53]
	s_mov_b32 s49, 0
	v_lshlrev_b32_e32 v170, 1, v18
	v_add_u32_e32 v250, 4, v210
	v_and_b32_e32 v250, 8, v250
	v_lshlrev_b32_e32 v250, 1, v250
	v_xor_b32_e32 v170, v170, v250
	v_mov_b32_e32 v17, v16
	v_mov_b32_e32 v18, v16
	v_mov_b32_e32 v19, v16
	v_mov_b32_e32 v20, v16
	v_mov_b32_e32 v21, v16
	v_mov_b32_e32 v22, v16
	v_mov_b32_e32 v23, v16
	v_mov_b32_e32 v24, v16
	v_mov_b32_e32 v25, v16
	v_mov_b32_e32 v26, v16
	v_mov_b32_e32 v27, v16
	v_mov_b32_e32 v28, v16
	v_mov_b32_e32 v29, v16
	v_mov_b32_e32 v30, v16
	v_mov_b32_e32 v31, v16
	v_mov_b32_e32 v52, v16
	v_mov_b32_e32 v53, v16
	v_mov_b32_e32 v54, v16
	v_mov_b32_e32 v55, v16
	v_mov_b32_e32 v60, v16
	v_mov_b32_e32 v61, v16
	v_mov_b32_e32 v62, v16
	v_mov_b32_e32 v63, v16
	v_mov_b32_e32 v68, v16
	v_mov_b32_e32 v69, v16
	v_mov_b32_e32 v70, v16
	v_mov_b32_e32 v71, v16
	v_mov_b32_e32 v76, v16
	v_mov_b32_e32 v77, v16
	v_mov_b32_e32 v78, v16
	v_mov_b32_e32 v79, v16
	v_mov_b32_e32 v48, v16
	v_mov_b32_e32 v49, v16
	v_mov_b32_e32 v50, v16
	v_mov_b32_e32 v51, v16
	v_mov_b32_e32 v56, v16
	v_mov_b32_e32 v57, v16
	v_mov_b32_e32 v58, v16
	v_mov_b32_e32 v59, v16
	v_mov_b32_e32 v64, v16
	v_mov_b32_e32 v65, v16
	v_mov_b32_e32 v66, v16
	v_mov_b32_e32 v67, v16
	v_mov_b32_e32 v72, v16
	v_mov_b32_e32 v73, v16
	v_mov_b32_e32 v74, v16
	v_mov_b32_e32 v75, v16
	v_mov_b32_e32 v84, v16
	v_mov_b32_e32 v85, v16
	v_mov_b32_e32 v86, v16
	v_mov_b32_e32 v87, v16
	v_mov_b32_e32 v92, v16
	v_mov_b32_e32 v93, v16
	v_mov_b32_e32 v94, v16
	v_mov_b32_e32 v95, v16
	v_mov_b32_e32 v100, v16
	v_mov_b32_e32 v101, v16
	v_mov_b32_e32 v102, v16
	v_mov_b32_e32 v103, v16
	v_mov_b32_e32 v108, v16
	v_mov_b32_e32 v109, v16
	v_mov_b32_e32 v110, v16
	v_mov_b32_e32 v111, v16
	v_mov_b32_e32 v80, v16
	v_mov_b32_e32 v81, v16
	v_mov_b32_e32 v82, v16
	v_mov_b32_e32 v83, v16
	v_mov_b32_e32 v88, v16
	v_mov_b32_e32 v89, v16
	v_mov_b32_e32 v90, v16
	v_mov_b32_e32 v91, v16
	v_mov_b32_e32 v96, v16
	v_mov_b32_e32 v97, v16
	v_mov_b32_e32 v98, v16
	v_mov_b32_e32 v99, v16
	v_mov_b32_e32 v104, v16
	v_mov_b32_e32 v105, v16
	v_mov_b32_e32 v106, v16
	v_mov_b32_e32 v107, v16
	v_mov_b32_e32 v116, v16
	v_mov_b32_e32 v117, v16
	v_mov_b32_e32 v118, v16
	v_mov_b32_e32 v119, v16
	v_mov_b32_e32 v124, v16
	v_mov_b32_e32 v125, v16
	v_mov_b32_e32 v126, v16
	v_mov_b32_e32 v127, v16
	v_mov_b32_e32 v136, v16
	v_mov_b32_e32 v137, v16
	v_mov_b32_e32 v138, v16
	v_mov_b32_e32 v139, v16
	v_mov_b32_e32 v140, v16
	v_mov_b32_e32 v141, v16
	v_mov_b32_e32 v142, v16
	v_mov_b32_e32 v143, v16
	v_mov_b32_e32 v112, v16
	v_mov_b32_e32 v113, v16
	v_mov_b32_e32 v114, v16
	v_mov_b32_e32 v115, v16
	v_mov_b32_e32 v120, v16
	v_mov_b32_e32 v121, v16
	v_mov_b32_e32 v122, v16
	v_mov_b32_e32 v123, v16
	v_mov_b32_e32 v128, v16
	v_mov_b32_e32 v129, v16
	v_mov_b32_e32 v130, v16
	v_mov_b32_e32 v131, v16
	v_mov_b32_e32 v132, v16
	v_mov_b32_e32 v133, v16
	v_mov_b32_e32 v134, v16
	v_mov_b32_e32 v135, v16
	v_mov_b32_e32 v144, v16
	v_mov_b32_e32 v145, v16
	v_mov_b32_e32 v146, v16
	v_mov_b32_e32 v147, v16
	v_mov_b32_e32 v148, v16
	v_mov_b32_e32 v149, v16
	v_mov_b32_e32 v150, v16
	v_mov_b32_e32 v151, v16
	v_mov_b32_e32 v152, v16
	v_mov_b32_e32 v153, v16
	v_mov_b32_e32 v154, v16
	v_mov_b32_e32 v155, v16
	v_mov_b32_e32 v156, v16
	v_mov_b32_e32 v157, v16
	v_mov_b32_e32 v158, v16
	v_mov_b32_e32 v159, v16
	s_waitcnt lgkmcnt(0)
	s_barrier
